# a+b plus P0 rmsnorm row loop: gain chunks kept in v174-233 (loaded once), in-loop reloads and their 15 vmcnt(0) store drains removed (de-serialised store ladder)
# speedup vs baseline: 1.0052x; 1.0007x over previous
; __device__ __forceinline__ void p0_prologue(const Args& a, LAS unsigned char* lds, int vcu, int G) {
;     ...
;     const float* x = a.in[0]; const f32x4* gm = (const f32x4*)a.in[1] + lane; bf16* H = (bf16*)(ws + WS_H);
;     { int m = nextrow(); f32x4 v[16], vn[16];
;       { const f32x4* xr = (const f32x4*)(x + (size_t)(m < M ? m : 0) * DM) + lane;
; #pragma unroll
;         for (int j = 0; j < 16; ++j) v[j] = __builtin_nontemporal_load(xr + 64 * j); }
;       while (m < M) {
;           const int mq = nextrow();
;           { const int mn = mq < M ? mq : m; const f32x4* xr = (const f32x4*)(x + (size_t)mn * DM) + lane;
; #pragma unroll
;             for (int j = 0; j < 16; ++j) vn[j] = __builtin_nontemporal_load(xr + 64 * j); }
;           float s = 0.f;
; #pragma unroll
;           for (int j = 0; j < 16; ++j) s += (v[j][0] * v[j][0] + v[j][1] * v[j][1]) + (v[j][2] * v[j][2] + v[j][3] * v[j][3]);
;           const float rs = 1.0f / sqrtf(wave_sum(s) * (1.0f / DM) + EPS);
.LBB0_154:
	s_load_dwordx16 s[48:63], s[0:1], 0x0
	s_ashr_i32 s11, s10, 31
	s_lshl_b64 s[2:3], s[10:11], 14
	v_lshlrev_b32_e32 v130, 4, v1
	v_mov_b32_e32 v131, 0
	s_waitcnt lgkmcnt(0)
	s_add_u32 s2, s48, s2
	s_addc_u32 s3, s49, s3
	s_waitcnt vmcnt(7)
	v_lshl_add_u64 v[34:35], s[2:3], 0, v[130:131]
	s_movk_i32 s14, 0x3000
	v_add_co_u32_e32 v14, vcc, s14, v34
	s_movk_i32 s15, 0x2000
	s_nop 0
	v_addc_co_u32_e32 v15, vcc, 0, v35, vcc
	s_waitcnt vmcnt(4)
	v_add_co_u32_e32 v30, vcc, s15, v34
	s_movk_i32 s16, 0x1000
	s_nop 0
	v_addc_co_u32_e32 v31, vcc, 0, v35, vcc
	v_add_co_u32_e32 v46, vcc, s16, v34
	global_load_dwordx4 v[2:5], v[14:15], off offset:3072 nt
	global_load_dwordx4 v[6:9], v[14:15], off offset:2048 nt
	global_load_dwordx4 v[10:13], v[14:15], off offset:1024 nt
	s_nop 0
	global_load_dwordx4 v[14:17], v[14:15], off nt
	v_addc_co_u32_e32 v47, vcc, 0, v35, vcc
	global_load_dwordx4 v[18:21], v[30:31], off offset:3072 nt
	global_load_dwordx4 v[22:25], v[30:31], off offset:2048 nt
	global_load_dwordx4 v[26:29], v[30:31], off offset:1024 nt
	s_nop 0
	global_load_dwordx4 v[30:33], v[30:31], off nt
	s_nop 0
	global_load_dwordx4 v[34:37], v[46:47], off offset:3072 nt
	global_load_dwordx4 v[38:41], v[46:47], off offset:2048 nt
	global_load_dwordx4 v[42:45], v[46:47], off offset:1024 nt
	s_nop 0
	global_load_dwordx4 v[46:49], v[46:47], off nt
	s_nop 0
	global_load_dwordx4 v[50:53], v130, s[2:3] offset:3072 nt
	global_load_dwordx4 v[54:57], v130, s[2:3] offset:2048 nt
	global_load_dwordx4 v[58:61], v130, s[2:3] offset:1024 nt
	global_load_dwordx4 v[62:65], v130, s[2:3] nt
	s_load_dwordx2 s[2:3], s[0:1], 0xc0
	v_lshlrev_b32_e32 v66, 3, v1
	v_mov_b32_e32 v67, v131
	v_lshl_add_u64 v[136:137], s[50:51], 0, v[130:131]
	v_lshl_add_u64 v[132:133], s[48:49], 0, v[130:131]
	s_waitcnt lgkmcnt(0)
	v_lshl_add_u64 v[66:67], s[2:3], 0, v[66:67]
	s_mov_b64 s[2:3], 0x22800000
	v_lshl_add_u64 v[134:135], v[66:67], 0, s[2:3]
	s_mov_b64 s[2:3], 0x1000
	v_lshl_add_u64 v[138:139], v[136:137], 0, s[2:3]
	s_mov_b64 s[2:3], 0x1400
	v_lshl_add_u64 v[140:141], v[136:137], 0, s[2:3]
	s_mov_b64 s[2:3], 0x1800
	v_lshl_add_u64 v[142:143], v[136:137], 0, s[2:3]
	s_mov_b64 s[2:3], 0x1c00
	v_lshl_add_u64 v[144:145], v[136:137], 0, s[2:3]
	s_mov_b64 s[2:3], 0x2000
	v_lshl_add_u64 v[146:147], v[136:137], 0, s[2:3]
	s_mov_b64 s[2:3], 0x2400
	v_lshl_add_u64 v[148:149], v[136:137], 0, s[2:3]
	s_mov_b64 s[2:3], 0x2800
	v_lshl_add_u64 v[150:151], v[136:137], 0, s[2:3]
	s_mov_b64 s[2:3], 0x2c00
	v_lshl_add_u64 v[152:153], v[136:137], 0, s[2:3]
	s_mov_b64 s[2:3], 0x3000
	v_lshl_add_u64 v[154:155], v[136:137], 0, s[2:3]
	s_mov_b64 s[2:3], 0x3400
	v_lshl_add_u64 v[156:157], v[136:137], 0, s[2:3]
	s_mov_b64 s[2:3], 0x3800
	v_lshl_add_u64 v[158:159], v[136:137], 0, s[2:3]
	s_mov_b64 s[2:3], 0x3c00
	v_mbcnt_lo_u32_b32 v66, -1, 0
	v_lshl_add_u64 v[160:161], v[136:137], 0, s[2:3]
	v_mov_b32_e32 v130, 0x358637bd
	s_mov_b32 s17, 0xf800000
	v_mov_b32_e32 v162, 0x260
	v_mbcnt_hi_u32_b32 v163, -1, v66
	global_load_dwordx4 v[174:177], v[136:137], off offset:1024
	global_load_dwordx4 v[178:181], v[136:137], off offset:2048
	global_load_dwordx4 v[182:185], v[136:137], off offset:3072
	global_load_dwordx4 v[186:189], v[138:139], off
	global_load_dwordx4 v[190:193], v[140:141], off
	global_load_dwordx4 v[194:197], v[142:143], off
	global_load_dwordx4 v[198:201], v[144:145], off
	global_load_dwordx4 v[202:205], v[146:147], off
	global_load_dwordx4 v[206:209], v[148:149], off
	global_load_dwordx4 v[210:213], v[150:151], off
	global_load_dwordx4 v[214:217], v[152:153], off
	global_load_dwordx4 v[218:221], v[154:155], off
	global_load_dwordx4 v[222:225], v[156:157], off
	global_load_dwordx4 v[226:229], v[158:159], off
	global_load_dwordx4 v[230:233], v[160:161], off
	s_branch .LBB0_156
.LBB0_155:
	s_waitcnt vmcnt(0)
	v_mul_f32_e32 v66, v63, v63
	v_mul_f32_e32 v67, v65, v65
	v_fmac_f32_e32 v66, v62, v62
	v_fmac_f32_e32 v67, v64, v64
	v_add_f32_e32 v66, v66, v67
	v_mul_f32_e32 v67, v59, v59
	v_mul_f32_e32 v68, v61, v61
	v_fmac_f32_e32 v67, v58, v58
	v_fmac_f32_e32 v68, v60, v60
	v_add_f32_e32 v67, v67, v68
	v_add_f32_e32 v66, v66, v67
	v_mul_f32_e32 v67, v55, v55
	v_mul_f32_e32 v68, v57, v57
	v_fmac_f32_e32 v67, v54, v54
	v_fmac_f32_e32 v68, v56, v56
	v_add_f32_e32 v67, v67, v68
	v_add_f32_e32 v66, v66, v67
	v_mul_f32_e32 v67, v51, v51
	v_mul_f32_e32 v68, v53, v53
	v_fmac_f32_e32 v67, v50, v50
	v_fmac_f32_e32 v68, v52, v52
	v_add_f32_e32 v67, v67, v68
	v_add_f32_e32 v66, v66, v67
	v_mul_f32_e32 v67, v47, v47
	v_mul_f32_e32 v68, v49, v49
	v_fmac_f32_e32 v67, v46, v46
	v_fmac_f32_e32 v68, v48, v48
	v_add_f32_e32 v67, v67, v68
	v_add_f32_e32 v66, v66, v67
	v_mul_f32_e32 v67, v43, v43
	v_mul_f32_e32 v68, v45, v45
	v_fmac_f32_e32 v67, v42, v42
	v_fmac_f32_e32 v68, v44, v44
	v_add_f32_e32 v67, v67, v68
	v_add_f32_e32 v66, v66, v67
	v_mul_f32_e32 v67, v39, v39
	v_mul_f32_e32 v68, v41, v41
	v_fmac_f32_e32 v67, v38, v38
	v_fmac_f32_e32 v68, v40, v40
	v_add_f32_e32 v67, v67, v68
	v_add_f32_e32 v66, v66, v67
	v_mul_f32_e32 v67, v35, v35
	v_mul_f32_e32 v68, v37, v37
	v_fmac_f32_e32 v67, v34, v34
	v_fmac_f32_e32 v68, v36, v36
	v_add_f32_e32 v67, v67, v68
	v_add_f32_e32 v66, v66, v67
	v_mul_f32_e32 v67, v31, v31
	v_mul_f32_e32 v68, v33, v33
	v_fmac_f32_e32 v67, v30, v30
	v_fmac_f32_e32 v68, v32, v32
	v_add_f32_e32 v67, v67, v68
	v_add_f32_e32 v66, v66, v67
	v_mul_f32_e32 v67, v27, v27
	v_mul_f32_e32 v68, v29, v29
	v_fmac_f32_e32 v67, v26, v26
	v_fmac_f32_e32 v68, v28, v28
	v_add_f32_e32 v67, v67, v68
	v_add_f32_e32 v66, v66, v67
	v_mul_f32_e32 v67, v23, v23
	v_mul_f32_e32 v68, v25, v25
	v_fmac_f32_e32 v67, v22, v22
	v_fmac_f32_e32 v68, v24, v24
	v_add_f32_e32 v67, v67, v68
	v_add_f32_e32 v66, v66, v67
	v_mul_f32_e32 v67, v19, v19
	v_mul_f32_e32 v68, v21, v21
	v_fmac_f32_e32 v67, v18, v18
	v_fmac_f32_e32 v68, v20, v20
	v_add_f32_e32 v67, v67, v68
	v_add_f32_e32 v66, v66, v67
	v_mul_f32_e32 v67, v15, v15
	v_mul_f32_e32 v68, v17, v17
	v_fmac_f32_e32 v67, v14, v14
	v_fmac_f32_e32 v68, v16, v16
	v_add_f32_e32 v67, v67, v68
	v_add_f32_e32 v66, v66, v67
	v_mul_f32_e32 v67, v11, v11
	v_mul_f32_e32 v68, v13, v13
	v_fmac_f32_e32 v67, v10, v10
	v_fmac_f32_e32 v68, v12, v12
	v_add_f32_e32 v67, v67, v68
	v_add_f32_e32 v66, v66, v67
	v_mul_f32_e32 v67, v7, v7
	v_mul_f32_e32 v68, v9, v9
	v_fmac_f32_e32 v67, v6, v6
	v_fmac_f32_e32 v68, v8, v8
	v_add_f32_e32 v67, v67, v68
	v_add_f32_e32 v66, v66, v67
	v_mul_f32_e32 v67, v3, v3
	v_mul_f32_e32 v68, v5, v5
	v_fmac_f32_e32 v67, v2, v2
	v_fmac_f32_e32 v68, v4, v4
	v_add_f32_e32 v67, v67, v68
	v_add_f32_e32 v66, v66, v67
	v_and_b32_e32 v67, 64, v163
	v_add_u32_e32 v100, 64, v67
	v_xor_b32_e32 v67, 1, v163
	v_cmp_lt_i32_e32 vcc, v67, v100
	s_cmpk_lt_i32 s12, 0x2000
	s_cselect_b64 s[2:3], -1, 0
	v_cndmask_b32_e32 v67, v163, v67, vcc
	v_lshlrev_b32_e32 v67, 2, v67
	ds_bpermute_b32 v67, v67, v66
	s_and_b64 s[4:5], s[2:3], exec
	s_cselect_b32 s2, s12, s10
	s_ashr_i32 s3, s2, 31
	s_lshl_b64 s[2:3], s[2:3], 14
	s_waitcnt lgkmcnt(0)
; __device__ __forceinline__ unsigned cvt_pk_bf16(float lo, float hi) { unsigned r; asm volatile("v_cvt_pk_bf16_f32 %0, %1, %2" : "=v"(r) : "v"(lo), "v"(hi)); return r; }
; __device__ __forceinline__ void p0_prologue(const Args& a, LAS unsigned char* lds, int vcu, int G) {
;     ...
;       while (m < M) {
;           const int mq = nextrow();
;           { const int mn = mq < M ? mq : m; const f32x4* xr = (const f32x4*)(x + (size_t)mn * DM) + lane;
; #pragma unroll
;             for (int j = 0; j < 16; ++j) vn[j] = __builtin_nontemporal_load(xr + 64 * j); }
;           float s = 0.f;
; #pragma unroll
;           for (int j = 0; j < 16; ++j) s += (v[j][0] * v[j][0] + v[j][1] * v[j][1]) + (v[j][2] * v[j][2] + v[j][3] * v[j][3]);
;           const float rs = 1.0f / sqrtf(wave_sum(s) * (1.0f / DM) + EPS);
;           u32x2* o = (u32x2*)(H + (size_t)m * DM) + lane;
; #pragma unroll
;           for (int j = 0; j < 16; ++j) { const f32x4 g = gm[64 * j]; u32x2 w; w.x = cvt_pk_bf16(v[j][0] * rs * g[0], v[j][1] * rs * g[1]); w.y = cvt_pk_bf16(v[j][2] * rs * g[2], v[j][3] * rs * g[3]); o[64 * j] = w; }
	v_add_f32_e32 v74, v66, v67
	v_xor_b32_e32 v66, 2, v163
	v_cmp_lt_i32_e32 vcc, v66, v100
	v_lshl_add_u64 v[98:99], v[132:133], 0, s[2:3]
	s_ashr_i32 s11, s10, 31
	v_cndmask_b32_e32 v66, v163, v66, vcc
	v_lshlrev_b32_e32 v66, 2, v66
	ds_bpermute_b32 v75, v66, v74
	global_load_dwordx4 v[66:69], v[98:99], off nt
	global_load_dwordx4 v[70:73], v[98:99], off offset:1024 nt
	global_load_dwordx4 v[122:125], v[136:137], off
	s_mov_b32 s18, s13
	s_waitcnt lgkmcnt(0)
	v_add_f32_e32 v82, v74, v75
	v_xor_b32_e32 v74, 4, v163
	v_cmp_lt_i32_e32 vcc, v74, v100
	s_nop 1
	v_cndmask_b32_e32 v74, v163, v74, vcc
	v_lshlrev_b32_e32 v74, 2, v74
	ds_bpermute_b32 v83, v74, v82
	v_add_co_u32_e32 v94, vcc, 0x1000, v98
	global_load_dwordx4 v[74:77], v[98:99], off offset:2048 nt
	global_load_dwordx4 v[78:81], v[98:99], off offset:3072 nt
	v_addc_co_u32_e32 v95, vcc, 0, v99, vcc
	s_waitcnt lgkmcnt(0)
	v_add_f32_e32 v90, v82, v83
	v_xor_b32_e32 v82, 8, v163
	v_cmp_lt_i32_e64 s[6:7], v82, v100
	s_nop 1
	v_cndmask_b32_e64 v82, v163, v82, s[6:7]
	v_lshlrev_b32_e32 v82, 2, v82
	ds_bpermute_b32 v91, v82, v90
	global_load_dwordx4 v[82:85], v[94:95], off nt
	global_load_dwordx4 v[86:89], v[94:95], off offset:1024 nt
	s_waitcnt lgkmcnt(0)
	v_add_f32_e32 v101, v90, v91
	v_xor_b32_e32 v90, 16, v163
	v_cmp_lt_i32_e32 vcc, v90, v100
	s_nop 1
	v_cndmask_b32_e32 v90, v163, v90, vcc
	v_lshlrev_b32_e32 v90, 2, v90
	ds_bpermute_b32 v102, v90, v101
	v_add_co_u32_e32 v110, vcc, s15, v98
	global_load_dwordx4 v[90:93], v[94:95], off offset:2048 nt
	s_nop 0
	global_load_dwordx4 v[94:97], v[94:95], off offset:3072 nt
	v_addc_co_u32_e32 v111, vcc, 0, v99, vcc
	s_waitcnt lgkmcnt(0)
	v_add_f32_e32 v101, v101, v102
	v_xor_b32_e32 v102, 32, v163
	v_cmp_lt_i32_e64 s[6:7], v102, v100
	v_add_co_u32_e32 v126, vcc, s14, v98
	s_nop 0
	v_cndmask_b32_e64 v100, v163, v102, s[6:7]
	v_lshlrev_b32_e32 v100, 2, v100
	ds_bpermute_b32 v100, v100, v101
	v_addc_co_u32_e32 v127, vcc, 0, v99, vcc
	s_waitcnt lgkmcnt(0)
	v_add_f32_e32 v98, v101, v100
	v_fmamk_f32 v98, v98, 0x39800000, v130
	v_mul_f32_e32 v100, 0x4f800000, v98
	v_cmp_gt_f32_e64 s[6:7], s17, v98
	s_nop 1
	v_cndmask_b32_e64 v98, v98, v100, s[6:7]
	v_sqrt_f32_e32 v100, v98
	s_nop 0
	v_add_u32_e32 v99, -1, v100
	v_fma_f32 v101, -v99, v100, v98
	v_cmp_ge_f32_e32 vcc, 0, v101
	v_add_u32_e32 v101, 1, v100
	s_nop 0
	v_cndmask_b32_e32 v99, v100, v99, vcc
	v_fma_f32 v100, -v101, v100, v98
	v_cmp_lt_f32_e32 vcc, 0, v100
	s_nop 1
	v_cndmask_b32_e32 v99, v99, v101, vcc
	v_mul_f32_e32 v100, 0x37800000, v99
	v_cndmask_b32_e64 v99, v99, v100, s[6:7]
	v_cmp_class_f32_e32 vcc, v98, v162
	s_mov_b64 s[6:7], s[8:9]
	s_nop 0
	v_cndmask_b32_e32 v128, v99, v98, vcc
	v_div_scale_f32 v129, s[2:3], v128, v128, 1.0
	v_rcp_f32_e32 v164, v129
	v_div_scale_f32 v165, vcc, 1.0, v128, 1.0
	s_lshl_b64 s[2:3], s[10:11], 13
	v_fma_f32 v114, -v129, v164, 1.0
	v_fmac_f32_e32 v164, v114, v164
	v_mul_f32_e32 v166, v165, v164
	v_fma_f32 v114, -v129, v166, v165
	v_fmac_f32_e32 v166, v114, v164
	v_fma_f32 v129, -v129, v166, v165
	v_div_fmas_f32 v129, v129, v164, v166
	v_div_fixup_f32 v170, v129, v128, 1.0
	v_mul_f32_e32 v62, v62, v170
	v_mul_f32_e32 v63, v63, v170
	s_waitcnt vmcnt(6)
	v_mul_f32_e32 v62, v122, v62
	v_mul_f32_e32 v63, v123, v63
	v_mul_f32_e32 v64, v64, v170
	v_mul_f32_e32 v65, v65, v170
	v_lshl_add_u64 v[164:165], v[134:135], 0, s[2:3]
	global_load_dwordx4 v[102:105], v[110:111], off offset:1024 nt
	global_load_dwordx4 v[106:109], v[110:111], off offset:2048 nt
	global_load_dwordx4 v[98:101], v[126:127], off offset:-4096 nt
	s_nop 0
	global_load_dwordx4 v[110:113], v[110:111], off offset:3072 nt
	s_nop 0
	global_load_dwordx4 v[114:117], v[126:127], off nt
	global_load_dwordx4 v[118:121], v[126:127], off offset:1024 nt
	v_mul_f32_e32 v64, v124, v64
	v_mul_f32_e32 v65, v125, v65
	global_load_dwordx4 v[122:125], v[126:127], off offset:2048 nt
	s_nop 0
	global_load_dwordx4 v[126:129], v[126:127], off offset:3072 nt
	v_cvt_pk_bf16_f32 v62, v62, v63
	v_cvt_pk_bf16_f32 v63, v64, v65
	global_store_dwordx2 v[164:165], v[62:63], off
	s_nop 1
	v_mov_b64_e32 v[62:63], v[174:175]
	v_mov_b64_e32 v[64:65], v[176:177]
	v_mul_f32_e32 v58, v58, v170
	v_mul_f32_e32 v59, v59, v170
	v_mul_f32_e32 v60, v60, v170
	v_mul_f32_e32 v61, v61, v170
	v_mul_f32_e32 v54, v54, v170
	v_mul_f32_e32 v55, v55, v170
	v_mul_f32_e32 v56, v56, v170
	v_mul_f32_e32 v57, v57, v170
	v_mul_f32_e32 v50, v50, v170
	v_mul_f32_e32 v51, v51, v170
	v_mul_f32_e32 v52, v52, v170
	v_mul_f32_e32 v53, v53, v170
	v_mul_f32_e32 v46, v46, v170
	v_mul_f32_e32 v47, v47, v170
	v_mul_f32_e32 v48, v48, v170
	v_mul_f32_e32 v49, v49, v170
	v_mul_f32_e32 v42, v42, v170
	v_mul_f32_e32 v43, v43, v170
	v_mul_f32_e32 v44, v44, v170
	v_mul_f32_e32 v45, v45, v170
	v_mul_f32_e32 v38, v38, v170
	v_mul_f32_e32 v39, v39, v170
	v_mul_f32_e32 v40, v40, v170
	v_mul_f32_e32 v41, v41, v170
	v_mul_f32_e32 v34, v34, v170
	v_mul_f32_e32 v35, v35, v170
	v_mul_f32_e32 v36, v36, v170
	v_mul_f32_e32 v37, v37, v170
	v_add_co_u32_e32 v168, vcc, s16, v164
	v_mul_f32_e32 v30, v30, v170
	v_mul_f32_e32 v31, v31, v170
	v_addc_co_u32_e32 v169, vcc, 0, v165, vcc
	v_mul_f32_e32 v32, v32, v170
	v_mul_f32_e32 v33, v33, v170
	v_mul_f32_e32 v26, v26, v170
	v_mul_f32_e32 v27, v27, v170
	v_mul_f32_e32 v28, v28, v170
	v_mul_f32_e32 v29, v29, v170
	v_mul_f32_e32 v22, v22, v170
	v_mul_f32_e32 v23, v23, v170
	v_mul_f32_e32 v24, v24, v170
	v_mul_f32_e32 v25, v25, v170
	v_mul_f32_e32 v18, v18, v170
	v_mul_f32_e32 v19, v19, v170
	v_mul_f32_e32 v20, v20, v170
	v_mul_f32_e32 v21, v21, v170
	v_mul_f32_e32 v14, v14, v170
	v_mul_f32_e32 v15, v15, v170
	v_mul_f32_e32 v16, v16, v170
	v_mul_f32_e32 v17, v17, v170
	v_mul_f32_e32 v10, v10, v170
	v_mul_f32_e32 v11, v11, v170
	v_mul_f32_e32 v12, v12, v170
	v_mul_f32_e32 v13, v13, v170
	v_mul_f32_e32 v6, v6, v170
	v_mul_f32_e32 v7, v7, v170
	v_mul_f32_e32 v8, v8, v170
	v_mul_f32_e32 v9, v9, v170
	v_mul_f32_e32 v171, v2, v170
	v_mul_f32_e32 v172, v3, v170
	v_mul_f32_e32 v173, v4, v170
	v_mul_f32_e32 v170, v5, v170
	s_mov_b32 s10, s12
	s_mov_b64 vcc, s[4:5]
	s_waitcnt vmcnt(1)
; __device__ __forceinline__ unsigned cvt_pk_bf16(float lo, float hi) { unsigned r; asm volatile("v_cvt_pk_bf16_f32 %0, %1, %2" : "=v"(r) : "v"(lo), "v"(hi)); return r; }
; __device__ __forceinline__ void p0_prologue(const Args& a, LAS unsigned char* lds, int vcu, int G) {
;     ...
;           u32x2* o = (u32x2*)(H + (size_t)m * DM) + lane;
; #pragma unroll
;           for (int j = 0; j < 16; ++j) { const f32x4 g = gm[64 * j]; u32x2 w; w.x = cvt_pk_bf16(v[j][0] * rs * g[0], v[j][1] * rs * g[1]); w.y = cvt_pk_bf16(v[j][2] * rs * g[2], v[j][3] * rs * g[3]); o[64 * j] = w; }
; #pragma unroll
;           for (int j = 0; j < 16; ++j) v[j] = vn[j];
	v_mov_b64_e32 v[2:3], v[126:127]
	v_mov_b64_e32 v[4:5], v[128:129]
	v_mul_f32_e32 v58, v62, v58
	v_mul_f32_e32 v59, v63, v59
	v_cvt_pk_bf16_f32 v58, v58, v59
	v_mul_f32_e32 v59, v64, v60
	v_mul_f32_e32 v60, v65, v61
	v_cvt_pk_bf16_f32 v59, v59, v60
	global_store_dwordx2 v[164:165], v[58:59], off offset:512
	s_nop 1
	v_mov_b64_e32 v[58:59], v[178:179]
	v_mov_b64_e32 v[60:61], v[180:181]
	v_mov_b64_e32 v[62:63], v[66:67]
	v_mov_b64_e32 v[64:65], v[68:69]
	v_mul_f32_e32 v54, v54, v58
	v_mul_f32_e32 v55, v55, v59
	v_mul_f32_e32 v56, v56, v60
	v_mul_f32_e32 v57, v57, v61
	v_cvt_pk_bf16_f32 v54, v54, v55
	v_cvt_pk_bf16_f32 v55, v56, v57
	global_store_dwordx2 v[164:165], v[54:55], off offset:1024
	s_nop 1
	v_mov_b64_e32 v[54:55], v[182:183]
	v_mov_b64_e32 v[56:57], v[184:185]
	v_mov_b64_e32 v[58:59], v[70:71]
	v_mov_b64_e32 v[60:61], v[72:73]
	v_mul_f32_e32 v50, v50, v54
	v_mul_f32_e32 v51, v51, v55
	v_mul_f32_e32 v52, v52, v56
	v_mul_f32_e32 v53, v53, v57
	v_cvt_pk_bf16_f32 v50, v50, v51
	v_cvt_pk_bf16_f32 v51, v52, v53
	global_store_dwordx2 v[164:165], v[50:51], off offset:1536
	s_nop 1
	v_mov_b64_e32 v[50:51], v[186:187]
	v_mov_b64_e32 v[52:53], v[188:189]
	v_mov_b64_e32 v[54:55], v[74:75]
	v_mov_b64_e32 v[56:57], v[76:77]
	v_mul_f32_e32 v46, v46, v50
	v_mul_f32_e32 v47, v47, v51
	v_mul_f32_e32 v48, v48, v52
	v_mul_f32_e32 v49, v49, v53
	v_cvt_pk_bf16_f32 v46, v46, v47
	v_cvt_pk_bf16_f32 v47, v48, v49
	global_store_dwordx2 v[164:165], v[46:47], off offset:2048
	s_nop 1
	v_mov_b64_e32 v[46:47], v[190:191]
	v_mov_b64_e32 v[48:49], v[192:193]
	v_mov_b64_e32 v[50:51], v[78:79]
	v_mov_b64_e32 v[52:53], v[80:81]
	v_mul_f32_e32 v42, v42, v46
	v_mul_f32_e32 v43, v43, v47
	v_mul_f32_e32 v44, v44, v48
	v_mul_f32_e32 v45, v45, v49
	v_cvt_pk_bf16_f32 v42, v42, v43
	v_cvt_pk_bf16_f32 v43, v44, v45
	global_store_dwordx2 v[164:165], v[42:43], off offset:2560
	s_nop 1
	v_mov_b64_e32 v[42:43], v[194:195]
	v_mov_b64_e32 v[44:45], v[196:197]
	v_mov_b64_e32 v[46:47], v[82:83]
	v_mov_b64_e32 v[48:49], v[84:85]
	v_mul_f32_e32 v38, v38, v42
	v_mul_f32_e32 v39, v39, v43
	v_mul_f32_e32 v40, v40, v44
	v_mul_f32_e32 v41, v41, v45
	v_cvt_pk_bf16_f32 v38, v38, v39
	v_cvt_pk_bf16_f32 v39, v40, v41
	global_store_dwordx2 v[164:165], v[38:39], off offset:3072
	s_nop 1
	v_mov_b64_e32 v[38:39], v[198:199]
	v_mov_b64_e32 v[40:41], v[200:201]
	v_mov_b64_e32 v[42:43], v[86:87]
	v_mov_b64_e32 v[44:45], v[88:89]
	v_mul_f32_e32 v34, v34, v38
	v_mul_f32_e32 v35, v35, v39
	v_mul_f32_e32 v36, v36, v40
	v_mul_f32_e32 v37, v37, v41
	v_cvt_pk_bf16_f32 v34, v34, v35
	v_cvt_pk_bf16_f32 v35, v36, v37
	global_store_dwordx2 v[164:165], v[34:35], off offset:3584
	s_nop 1
	v_mov_b64_e32 v[34:35], v[202:203]
	v_mov_b64_e32 v[36:37], v[204:205]
	v_mov_b64_e32 v[38:39], v[90:91]
	v_mov_b64_e32 v[40:41], v[92:93]
	v_mul_f32_e32 v30, v30, v34
	v_mul_f32_e32 v31, v31, v35
	v_mul_f32_e32 v32, v32, v36
	v_mul_f32_e32 v33, v33, v37
	v_cvt_pk_bf16_f32 v30, v30, v31
	v_cvt_pk_bf16_f32 v31, v32, v33
	global_store_dwordx2 v[168:169], v[30:31], off
	s_nop 1
	v_mov_b64_e32 v[30:31], v[206:207]
	v_mov_b64_e32 v[32:33], v[208:209]
	v_mov_b64_e32 v[34:35], v[94:95]
	v_mov_b64_e32 v[36:37], v[96:97]
	v_mul_f32_e32 v26, v26, v30
	v_mul_f32_e32 v27, v27, v31
	v_mul_f32_e32 v28, v28, v32
	v_mul_f32_e32 v29, v29, v33
	v_cvt_pk_bf16_f32 v26, v26, v27
	v_cvt_pk_bf16_f32 v27, v28, v29
	global_store_dwordx2 v[168:169], v[26:27], off offset:512
	s_nop 1
	v_mov_b64_e32 v[26:27], v[210:211]
	v_mov_b64_e32 v[28:29], v[212:213]
	v_mov_b64_e32 v[30:31], v[98:99]
	v_mov_b64_e32 v[32:33], v[100:101]
	v_mul_f32_e32 v22, v22, v26
	v_mul_f32_e32 v23, v23, v27
	v_mul_f32_e32 v24, v24, v28
	v_mul_f32_e32 v25, v25, v29
	v_cvt_pk_bf16_f32 v22, v22, v23
	v_cvt_pk_bf16_f32 v23, v24, v25
	global_store_dwordx2 v[168:169], v[22:23], off offset:1024
	s_nop 1
	v_mov_b64_e32 v[22:23], v[214:215]
	v_mov_b64_e32 v[24:25], v[216:217]
	v_mov_b64_e32 v[26:27], v[102:103]
	v_mov_b64_e32 v[28:29], v[104:105]
	v_mul_f32_e32 v18, v18, v22
	v_mul_f32_e32 v19, v19, v23
	v_mul_f32_e32 v20, v20, v24
	v_mul_f32_e32 v21, v21, v25
	v_cvt_pk_bf16_f32 v18, v18, v19
	v_cvt_pk_bf16_f32 v19, v20, v21
	global_store_dwordx2 v[168:169], v[18:19], off offset:1536
	s_nop 1
	v_mov_b64_e32 v[18:19], v[218:219]
	v_mov_b64_e32 v[20:21], v[220:221]
	v_mov_b64_e32 v[22:23], v[106:107]
	v_mov_b64_e32 v[24:25], v[108:109]
	v_mul_f32_e32 v14, v14, v18
	v_mul_f32_e32 v15, v15, v19
	v_mul_f32_e32 v16, v16, v20
	v_mul_f32_e32 v17, v17, v21
	v_cvt_pk_bf16_f32 v14, v14, v15
	v_cvt_pk_bf16_f32 v15, v16, v17
	global_store_dwordx2 v[168:169], v[14:15], off offset:2048
	s_nop 1
	v_mov_b64_e32 v[14:15], v[222:223]
	v_mov_b64_e32 v[16:17], v[224:225]
	v_mov_b64_e32 v[18:19], v[110:111]
	v_mov_b64_e32 v[20:21], v[112:113]
	v_mul_f32_e32 v10, v10, v14
	v_mul_f32_e32 v11, v11, v15
	v_mul_f32_e32 v12, v12, v16
	v_mul_f32_e32 v13, v13, v17
	v_cvt_pk_bf16_f32 v10, v10, v11
	v_cvt_pk_bf16_f32 v11, v12, v13
	global_store_dwordx2 v[168:169], v[10:11], off offset:2560
	s_nop 1
	v_mov_b64_e32 v[10:11], v[226:227]
	v_mov_b64_e32 v[12:13], v[228:229]
	v_mov_b64_e32 v[14:15], v[114:115]
	v_mov_b64_e32 v[16:17], v[116:117]
	v_mul_f32_e32 v6, v6, v10
	v_mul_f32_e32 v7, v7, v11
	v_mul_f32_e32 v8, v8, v12
	v_mul_f32_e32 v9, v9, v13
	v_cvt_pk_bf16_f32 v6, v6, v7
	v_cvt_pk_bf16_f32 v7, v8, v9
	global_store_dwordx2 v[168:169], v[6:7], off offset:3072
	s_nop 1
	v_mov_b64_e32 v[164:165], v[230:231]
	v_mov_b64_e32 v[166:167], v[232:233]
	v_mov_b64_e32 v[10:11], v[118:119]
	v_mov_b64_e32 v[6:7], v[122:123]
	v_mov_b64_e32 v[12:13], v[120:121]
	v_mov_b64_e32 v[8:9], v[124:125]
	v_mul_f32_e32 v66, v171, v164
	v_mul_f32_e32 v67, v172, v165
	v_mul_f32_e32 v68, v173, v166
	v_mul_f32_e32 v69, v170, v167
	v_cvt_pk_bf16_f32 v66, v66, v67
	v_cvt_pk_bf16_f32 v67, v68, v69
	global_store_dwordx2 v[168:169], v[66:67], off offset:3584
	s_cbranch_vccz .LBB0_179
